# in-proj GEMM: lean branch-free epilogue (identity and silu tiles): in-place bf16 pack, chained 64-bit addresses, 16 stores
# speedup vs baseline: 1.0040x; 1.0004x over previous
; #define GAS __attribute__((address_space(1)))
; __device__ __forceinline__ unsigned cvt_pk_bf16(float lo, float hi) { const f32x2_t_ v = {lo, hi}; const bf16x2_t_ b = __builtin_convertvector(v, bf16x2_t_); return __builtin_bit_cast(unsigned, b); }
;     __device__ __forceinline__ void operator()(const f32x4 (&acc)[2][2][4][2], const pg8::GUnit& u, int wr, int wc, int fr, int fq) const {
;         bf16_t* base; int ldc, mode = 0, bjs = 128; int rowb = u.pm * 256 + wr * 64 + fr, colb = u.pn * 256 + wc * 32 + 8 * fq;
;         if (u.kind == 0) { base = P; ldc = INW; const int pn = u.pn; if (pn >= GA / 256) mode = 1; else if ((pn >= ZA / 256 && pn < QB / 256) || (pn >= ZB / 256 && pn < QM / 256) || (pn >= ZM / 256)) mode = 2;
;             if (GATES_FP8) {
;                 int nh = 0, hp = 0; size_t off = 0;
;                 if (pn >= KA / 256 && pn < VA / 256) { nh = 12; hp = pn - KA / 256; off = WS_KNA; } else if (pn >= VA / 256 && pn < ZA / 256) { nh = 12; hp = pn - VA / 256; off = WS_VNA; }
;                 else if (pn >= KB / 256 && pn < VB / 256) { nh = 4; hp = pn - KB / 256; off = WS_KSW; } else if (pn >= VB / 256 && pn < ZB / 256) { nh = 4; hp = pn - VB / 256; off = WS_VSW; }
;                 if (nh) { const int b = u.pm >> 3; base = wsb16 + off / 2; ldc = 128; bjs = SEQ * 128; rowb = (b * nh + 2 * hp) * SEQ + (u.pm & 7) * 256 + wr * 64 + fr; colb = wc * 32 + 8 * fq; } } }
;         else { base = (u.kind == 1) ? KVM0 : KVM1; ldc = KVW; }
; #pragma unroll
;         for (int ai = 0; ai < 2; ++ai)
; #pragma unroll
;             for (int m = 0; m < 4; ++m) { GAS bf16_t* rowp = (GAS bf16_t*)base + (size_t)(rowb + ai * 128 + m * 16) * ldc + colb;
; #pragma unroll
;                 for (int bj = 0; bj < 2; ++bj) { f32x4 v0 = acc[ai][bj][m][0], v1 = acc[ai][bj][m][1];
;                     if (mode == 1) {
; #pragma unroll
;                         for (int j = 0; j < 4; ++j) { v0[j] = sigmoid_f(v0[j]); v1[j] = sigmoid_f(v1[j]); } }
;                     else if (mode == 2) {
; #pragma unroll
;                         for (int j = 0; j < 4; ++j) { v0[j] = v0[j] * sigmoid_f(v0[j]); v1[j] = v1[j] * sigmoid_f(v1[j]); } }
;                     u32x4 w; w.x = cvt_pk_bf16(v0[0], v0[1]); w.y = cvt_pk_bf16(v0[2], v0[3]); w.z = cvt_pk_bf16(v1[0], v1[1]); w.w = cvt_pk_bf16(v1[2], v1[3]);
;                     *(GAS u32x4*)(rowp + (size_t)bj * bjs) = w; } }
.Lin_epi_fast:
	v_ashrrev_i32_e32 v154, 1, v0
	v_and_b32_e32 v154, -8, v154
	v_add_u32_e32 v154, s18, v154
	v_and_or_b32 v0, v0, 15, s3
	v_add_u32_e32 v0, s13, v0
	v_ashrrev_i32_e32 v155, 31, v154
	v_lshl_add_u64 v[154:155], v[154:155], 1, v[138:139]
	v_mad_i64_i32 v[156:157], vcc, s4, v0, 0
	v_lshl_add_u64 v[156:157], v[156:157], 1, v[154:155]
	s_lshl_b64 s[10:11], s[4:5], 5
	s_lshl_b64 s[8:9], s[8:9], 1
	s_lshl_b64 s[4:5], s[4:5], 8
	v_lshl_add_u64 v[160:161], v[156:157], 0, s[4:5]
	v_cvt_pk_bf16_f32 v126, v126, v127
	v_cvt_pk_bf16_f32 v127, v128, v129
	v_cvt_pk_bf16_f32 v128, v122, v123
	v_cvt_pk_bf16_f32 v129, v124, v125
	v_lshl_add_u64 v[158:159], v[156:157], 0, s[8:9]
	global_store_dwordx4 v[156:157], v[126:129], off
	v_cvt_pk_bf16_f32 v118, v118, v119
	v_cvt_pk_bf16_f32 v119, v120, v121
	v_cvt_pk_bf16_f32 v120, v114, v115
	v_cvt_pk_bf16_f32 v121, v116, v117
	global_store_dwordx4 v[158:159], v[118:121], off
	v_lshl_add_u64 v[156:157], v[156:157], 0, s[10:11]
	v_cvt_pk_bf16_f32 v110, v110, v111
	v_cvt_pk_bf16_f32 v111, v112, v113
	v_cvt_pk_bf16_f32 v112, v106, v107
	v_cvt_pk_bf16_f32 v113, v108, v109
	v_lshl_add_u64 v[158:159], v[156:157], 0, s[8:9]
	global_store_dwordx4 v[156:157], v[110:113], off
	v_cvt_pk_bf16_f32 v102, v102, v103
	v_cvt_pk_bf16_f32 v103, v104, v105
	v_cvt_pk_bf16_f32 v104, v98, v99
	v_cvt_pk_bf16_f32 v105, v100, v101
	global_store_dwordx4 v[158:159], v[102:105], off
	v_lshl_add_u64 v[156:157], v[156:157], 0, s[10:11]
	v_cvt_pk_bf16_f32 v94, v94, v95
	v_cvt_pk_bf16_f32 v95, v96, v97
	v_cvt_pk_bf16_f32 v96, v90, v91
	v_cvt_pk_bf16_f32 v97, v92, v93
	v_lshl_add_u64 v[158:159], v[156:157], 0, s[8:9]
	global_store_dwordx4 v[156:157], v[94:97], off
	v_cvt_pk_bf16_f32 v86, v86, v87
	v_cvt_pk_bf16_f32 v87, v88, v89
	v_cvt_pk_bf16_f32 v88, v82, v83
	v_cvt_pk_bf16_f32 v89, v84, v85
	global_store_dwordx4 v[158:159], v[86:89], off
	v_lshl_add_u64 v[156:157], v[156:157], 0, s[10:11]
	v_cvt_pk_bf16_f32 v78, v78, v79
	v_cvt_pk_bf16_f32 v79, v80, v81
	v_cvt_pk_bf16_f32 v80, v74, v75
	v_cvt_pk_bf16_f32 v81, v76, v77
	v_lshl_add_u64 v[158:159], v[156:157], 0, s[8:9]
	global_store_dwordx4 v[156:157], v[78:81], off
	v_cvt_pk_bf16_f32 v70, v70, v71
	v_cvt_pk_bf16_f32 v71, v72, v73
	v_cvt_pk_bf16_f32 v72, v66, v67
	v_cvt_pk_bf16_f32 v73, v68, v69
	global_store_dwordx4 v[158:159], v[70:73], off
	v_mov_b64_e32 v[156:157], v[160:161]
	v_cvt_pk_bf16_f32 v62, v62, v63
	v_cvt_pk_bf16_f32 v63, v64, v65
	v_cvt_pk_bf16_f32 v64, v58, v59
	v_cvt_pk_bf16_f32 v65, v60, v61
	v_lshl_add_u64 v[158:159], v[156:157], 0, s[8:9]
	global_store_dwordx4 v[156:157], v[62:65], off
	v_cvt_pk_bf16_f32 v54, v54, v55
	v_cvt_pk_bf16_f32 v55, v56, v57
	v_cvt_pk_bf16_f32 v56, v50, v51
	v_cvt_pk_bf16_f32 v57, v52, v53
	global_store_dwordx4 v[158:159], v[54:57], off
	v_lshl_add_u64 v[156:157], v[156:157], 0, s[10:11]
	v_cvt_pk_bf16_f32 v46, v46, v47
	v_cvt_pk_bf16_f32 v47, v48, v49
	v_cvt_pk_bf16_f32 v48, v42, v43
	v_cvt_pk_bf16_f32 v49, v44, v45
	v_lshl_add_u64 v[158:159], v[156:157], 0, s[8:9]
	global_store_dwordx4 v[156:157], v[46:49], off
	v_cvt_pk_bf16_f32 v38, v38, v39
	v_cvt_pk_bf16_f32 v39, v40, v41
	v_cvt_pk_bf16_f32 v40, v34, v35
	v_cvt_pk_bf16_f32 v41, v36, v37
	global_store_dwordx4 v[158:159], v[38:41], off
	v_lshl_add_u64 v[156:157], v[156:157], 0, s[10:11]
	v_cvt_pk_bf16_f32 v30, v30, v31
	v_cvt_pk_bf16_f32 v31, v32, v33
	v_cvt_pk_bf16_f32 v32, v26, v27
	v_cvt_pk_bf16_f32 v33, v28, v29
	v_lshl_add_u64 v[158:159], v[156:157], 0, s[8:9]
	global_store_dwordx4 v[156:157], v[30:33], off
	v_cvt_pk_bf16_f32 v22, v22, v23
	v_cvt_pk_bf16_f32 v23, v24, v25
	v_cvt_pk_bf16_f32 v24, v18, v19
	v_cvt_pk_bf16_f32 v25, v20, v21
	global_store_dwordx4 v[158:159], v[22:25], off
	v_lshl_add_u64 v[156:157], v[156:157], 0, s[10:11]
	v_cvt_pk_bf16_f32 v14, v14, v15
	v_cvt_pk_bf16_f32 v15, v16, v17
	v_cvt_pk_bf16_f32 v16, v10, v11
	v_cvt_pk_bf16_f32 v17, v12, v13
	v_lshl_add_u64 v[158:159], v[156:157], 0, s[8:9]
	global_store_dwordx4 v[156:157], v[14:17], off
	v_cvt_pk_bf16_f32 v6, v6, v7
	v_cvt_pk_bf16_f32 v7, v8, v9
	v_cvt_pk_bf16_f32 v8, v2, v3
	v_cvt_pk_bf16_f32 v9, v4, v5
	global_store_dwordx4 v[158:159], v[6:9], off
	v_mov_b32_e32 v126, v210
	s_and_b64 vcc, exec, s[36:37]
	s_mov_b32 s18, s88
	s_mov_b32 s12, s87
	s_mov_b32 s13, s89
	s_mov_b32 s10, s91
	s_mov_b32 s11, s90
	s_cbranch_vccnz .LBB0_401
	s_branch .LBB0_273
; #define GAS __attribute__((address_space(1)))
; __device__ __forceinline__ float sigmoid_f(float x) { return __builtin_amdgcn_rcpf(1.0f + __builtin_amdgcn_exp2f(-x * LOG2E)); }
;     __device__ __forceinline__ void operator()(const f32x4 (&acc)[2][2][4][2], const pg8::GUnit& u, int wr, int wc, int fr, int fq) const {
;         bf16_t* base; int ldc, mode = 0, bjs = 128; int rowb = u.pm * 256 + wr * 64 + fr, colb = u.pn * 256 + wc * 32 + 8 * fq;
;         if (u.kind == 0) { base = P; ldc = INW; const int pn = u.pn; if (pn >= GA / 256) mode = 1; else if ((pn >= ZA / 256 && pn < QB / 256) || (pn >= ZB / 256 && pn < QM / 256) || (pn >= ZM / 256)) mode = 2;
;             if (GATES_FP8) {
;                 int nh = 0, hp = 0; size_t off = 0;
;                 if (pn >= KA / 256 && pn < VA / 256) { nh = 12; hp = pn - KA / 256; off = WS_KNA; } else if (pn >= VA / 256 && pn < ZA / 256) { nh = 12; hp = pn - VA / 256; off = WS_VNA; }
;                 else if (pn >= KB / 256 && pn < VB / 256) { nh = 4; hp = pn - KB / 256; off = WS_KSW; } else if (pn >= VB / 256 && pn < ZB / 256) { nh = 4; hp = pn - VB / 256; off = WS_VSW; }
;                 if (nh) { const int b = u.pm >> 3; base = wsb16 + off / 2; ldc = 128; bjs = SEQ * 128; rowb = (b * nh + 2 * hp) * SEQ + (u.pm & 7) * 256 + wr * 64 + fr; colb = wc * 32 + 8 * fq; } } }
;         else { base = (u.kind == 1) ? KVM0 : KVM1; ldc = KVW; }
; #pragma unroll
;         for (int ai = 0; ai < 2; ++ai)
; #pragma unroll
;             for (int m = 0; m < 4; ++m) { GAS bf16_t* rowp = (GAS bf16_t*)base + (size_t)(rowb + ai * 128 + m * 16) * ldc + colb;
; #pragma unroll
;                 for (int bj = 0; bj < 2; ++bj) { f32x4 v0 = acc[ai][bj][m][0], v1 = acc[ai][bj][m][1];
;                     if (mode == 1) {
; #pragma unroll
;                         for (int j = 0; j < 4; ++j) { v0[j] = sigmoid_f(v0[j]); v1[j] = sigmoid_f(v1[j]); } }
;                     else if (mode == 2) {
; #pragma unroll
;                         for (int j = 0; j < 4; ++j) { v0[j] = v0[j] * sigmoid_f(v0[j]); v1[j] = v1[j] * sigmoid_f(v1[j]); } }
;                     u32x4 w; w.x = cvt_pk_bf16(v0[0], v0[1]); w.y = cvt_pk_bf16(v0[2], v0[3]); w.z = cvt_pk_bf16(v1[0], v1[1]); w.w = cvt_pk_bf16(v1[2], v1[3]);
;                     *(GAS u32x4*)(rowp + (size_t)bj * bjs) = w; } }
.Lin_epi_fast_silu:
	v_ashrrev_i32_e32 v154, 1, v0
	v_and_b32_e32 v154, -8, v154
	v_add_u32_e32 v154, s18, v154
	v_and_or_b32 v0, v0, 15, s3
	v_add_u32_e32 v0, s13, v0
	v_ashrrev_i32_e32 v155, 31, v154
	v_lshl_add_u64 v[154:155], v[154:155], 1, v[138:139]
	v_mad_i64_i32 v[156:157], vcc, s4, v0, 0
	v_lshl_add_u64 v[156:157], v[156:157], 1, v[154:155]
	s_lshl_b64 s[10:11], s[4:5], 5
	s_lshl_b64 s[8:9], s[8:9], 1
	s_lshl_b64 s[4:5], s[4:5], 8
	v_lshl_add_u64 v[160:161], v[156:157], 0, s[4:5]
	v_mul_f32_e32 v162, 0xbfb8aa3b, v114
	v_mul_f32_e32 v163, 0xbfb8aa3b, v115
	v_mul_f32_e32 v164, 0xbfb8aa3b, v116
	v_mul_f32_e32 v165, 0xbfb8aa3b, v117
	v_mul_f32_e32 v166, 0xbfb8aa3b, v118
	v_mul_f32_e32 v167, 0xbfb8aa3b, v119
	v_mul_f32_e32 v168, 0xbfb8aa3b, v120
	v_mul_f32_e32 v169, 0xbfb8aa3b, v121
	v_mul_f32_e32 v170, 0xbfb8aa3b, v122
	v_mul_f32_e32 v171, 0xbfb8aa3b, v123
	v_mul_f32_e32 v172, 0xbfb8aa3b, v124
	v_mul_f32_e32 v173, 0xbfb8aa3b, v125
	v_mul_f32_e32 v174, 0xbfb8aa3b, v126
	v_mul_f32_e32 v175, 0xbfb8aa3b, v127
	v_mul_f32_e32 v176, 0xbfb8aa3b, v128
	v_mul_f32_e32 v177, 0xbfb8aa3b, v129
	v_exp_f32_e32 v162, v162
	v_exp_f32_e32 v163, v163
	v_exp_f32_e32 v164, v164
	v_exp_f32_e32 v165, v165
	v_exp_f32_e32 v166, v166
	v_exp_f32_e32 v167, v167
	v_exp_f32_e32 v168, v168
	v_exp_f32_e32 v169, v169
	v_exp_f32_e32 v170, v170
	v_exp_f32_e32 v171, v171
	v_exp_f32_e32 v172, v172
	v_exp_f32_e32 v173, v173
	v_exp_f32_e32 v174, v174
	v_exp_f32_e32 v175, v175
	v_exp_f32_e32 v176, v176
	v_exp_f32_e32 v177, v177
	v_add_f32_e32 v162, 1.0, v162
	v_add_f32_e32 v163, 1.0, v163
	v_add_f32_e32 v164, 1.0, v164
	v_add_f32_e32 v165, 1.0, v165
	v_add_f32_e32 v166, 1.0, v166
	v_add_f32_e32 v167, 1.0, v167
	v_add_f32_e32 v168, 1.0, v168
	v_add_f32_e32 v169, 1.0, v169
	v_add_f32_e32 v170, 1.0, v170
	v_add_f32_e32 v171, 1.0, v171
	v_add_f32_e32 v172, 1.0, v172
	v_add_f32_e32 v173, 1.0, v173
	v_add_f32_e32 v174, 1.0, v174
	v_add_f32_e32 v175, 1.0, v175
	v_add_f32_e32 v176, 1.0, v176
	v_add_f32_e32 v177, 1.0, v177
	v_rcp_f32_e32 v162, v162
	v_rcp_f32_e32 v163, v163
	v_rcp_f32_e32 v164, v164
	v_rcp_f32_e32 v165, v165
	v_rcp_f32_e32 v166, v166
	v_rcp_f32_e32 v167, v167
	v_rcp_f32_e32 v168, v168
	v_rcp_f32_e32 v169, v169
	v_rcp_f32_e32 v170, v170
	v_rcp_f32_e32 v171, v171
	v_rcp_f32_e32 v172, v172
	v_rcp_f32_e32 v173, v173
	v_rcp_f32_e32 v174, v174
	v_rcp_f32_e32 v175, v175
	v_rcp_f32_e32 v176, v176
	v_rcp_f32_e32 v177, v177
	v_mul_f32_e32 v114, v114, v162
	v_mul_f32_e32 v115, v115, v163
	v_mul_f32_e32 v116, v116, v164
	v_mul_f32_e32 v117, v117, v165
	v_mul_f32_e32 v118, v118, v166
	v_mul_f32_e32 v119, v119, v167
	v_mul_f32_e32 v120, v120, v168
	v_mul_f32_e32 v121, v121, v169
	v_mul_f32_e32 v122, v122, v170
	v_mul_f32_e32 v123, v123, v171
	v_mul_f32_e32 v124, v124, v172
	v_mul_f32_e32 v125, v125, v173
	v_mul_f32_e32 v126, v126, v174
	v_mul_f32_e32 v127, v127, v175
	v_mul_f32_e32 v128, v128, v176
	v_mul_f32_e32 v129, v129, v177
	v_cvt_pk_bf16_f32 v126, v126, v127
	v_cvt_pk_bf16_f32 v127, v128, v129
	v_cvt_pk_bf16_f32 v128, v122, v123
	v_cvt_pk_bf16_f32 v129, v124, v125
	v_lshl_add_u64 v[158:159], v[156:157], 0, s[8:9]
	global_store_dwordx4 v[156:157], v[126:129], off
	v_cvt_pk_bf16_f32 v118, v118, v119
	v_cvt_pk_bf16_f32 v119, v120, v121
	v_cvt_pk_bf16_f32 v120, v114, v115
	v_cvt_pk_bf16_f32 v121, v116, v117
	global_store_dwordx4 v[158:159], v[118:121], off
	v_lshl_add_u64 v[156:157], v[156:157], 0, s[10:11]
	v_mul_f32_e32 v162, 0xbfb8aa3b, v98
	v_mul_f32_e32 v163, 0xbfb8aa3b, v99
	v_mul_f32_e32 v164, 0xbfb8aa3b, v100
	v_mul_f32_e32 v165, 0xbfb8aa3b, v101
	v_mul_f32_e32 v166, 0xbfb8aa3b, v102
	v_mul_f32_e32 v167, 0xbfb8aa3b, v103
	v_mul_f32_e32 v168, 0xbfb8aa3b, v104
	v_mul_f32_e32 v169, 0xbfb8aa3b, v105
	v_mul_f32_e32 v170, 0xbfb8aa3b, v106
	v_mul_f32_e32 v171, 0xbfb8aa3b, v107
	v_mul_f32_e32 v172, 0xbfb8aa3b, v108
	v_mul_f32_e32 v173, 0xbfb8aa3b, v109
	v_mul_f32_e32 v174, 0xbfb8aa3b, v110
	v_mul_f32_e32 v175, 0xbfb8aa3b, v111
	v_mul_f32_e32 v176, 0xbfb8aa3b, v112
	v_mul_f32_e32 v177, 0xbfb8aa3b, v113
	v_exp_f32_e32 v162, v162
	v_exp_f32_e32 v163, v163
	v_exp_f32_e32 v164, v164
	v_exp_f32_e32 v165, v165
	v_exp_f32_e32 v166, v166
	v_exp_f32_e32 v167, v167
	v_exp_f32_e32 v168, v168
	v_exp_f32_e32 v169, v169
	v_exp_f32_e32 v170, v170
	v_exp_f32_e32 v171, v171
	v_exp_f32_e32 v172, v172
	v_exp_f32_e32 v173, v173
	v_exp_f32_e32 v174, v174
	v_exp_f32_e32 v175, v175
	v_exp_f32_e32 v176, v176
	v_exp_f32_e32 v177, v177
	v_add_f32_e32 v162, 1.0, v162
	v_add_f32_e32 v163, 1.0, v163
	v_add_f32_e32 v164, 1.0, v164
	v_add_f32_e32 v165, 1.0, v165
	v_add_f32_e32 v166, 1.0, v166
	v_add_f32_e32 v167, 1.0, v167
	v_add_f32_e32 v168, 1.0, v168
	v_add_f32_e32 v169, 1.0, v169
	v_add_f32_e32 v170, 1.0, v170
	v_add_f32_e32 v171, 1.0, v171
	v_add_f32_e32 v172, 1.0, v172
	v_add_f32_e32 v173, 1.0, v173
	v_add_f32_e32 v174, 1.0, v174
	v_add_f32_e32 v175, 1.0, v175
	v_add_f32_e32 v176, 1.0, v176
	v_add_f32_e32 v177, 1.0, v177
	v_rcp_f32_e32 v162, v162
	v_rcp_f32_e32 v163, v163
	v_rcp_f32_e32 v164, v164
	v_rcp_f32_e32 v165, v165
	v_rcp_f32_e32 v166, v166
	v_rcp_f32_e32 v167, v167
	v_rcp_f32_e32 v168, v168
	v_rcp_f32_e32 v169, v169
	v_rcp_f32_e32 v170, v170
	v_rcp_f32_e32 v171, v171
	v_rcp_f32_e32 v172, v172
	v_rcp_f32_e32 v173, v173
	v_rcp_f32_e32 v174, v174
	v_rcp_f32_e32 v175, v175
	v_rcp_f32_e32 v176, v176
	v_rcp_f32_e32 v177, v177
	v_mul_f32_e32 v98, v98, v162
	v_mul_f32_e32 v99, v99, v163
	v_mul_f32_e32 v100, v100, v164
	v_mul_f32_e32 v101, v101, v165
	v_mul_f32_e32 v102, v102, v166
	v_mul_f32_e32 v103, v103, v167
	v_mul_f32_e32 v104, v104, v168
	v_mul_f32_e32 v105, v105, v169
	v_mul_f32_e32 v106, v106, v170
; #define GAS __attribute__((address_space(1)))
; __device__ __forceinline__ unsigned cvt_pk_bf16(float lo, float hi) { const f32x2_t_ v = {lo, hi}; const bf16x2_t_ b = __builtin_convertvector(v, bf16x2_t_); return __builtin_bit_cast(unsigned, b); }
; __device__ __forceinline__ float sigmoid_f(float x) { return __builtin_amdgcn_rcpf(1.0f + __builtin_amdgcn_exp2f(-x * LOG2E)); }
;     __device__ __forceinline__ void operator()(const f32x4 (&acc)[2][2][4][2], const pg8::GUnit& u, int wr, int wc, int fr, int fq) const {
;     ...
;                 for (int bj = 0; bj < 2; ++bj) { f32x4 v0 = acc[ai][bj][m][0], v1 = acc[ai][bj][m][1];
;                     if (mode == 1) {
; #pragma unroll
;                         for (int j = 0; j < 4; ++j) { v0[j] = sigmoid_f(v0[j]); v1[j] = sigmoid_f(v1[j]); } }
;                     else if (mode == 2) {
; #pragma unroll
;                         for (int j = 0; j < 4; ++j) { v0[j] = v0[j] * sigmoid_f(v0[j]); v1[j] = v1[j] * sigmoid_f(v1[j]); } }
;                     u32x4 w; w.x = cvt_pk_bf16(v0[0], v0[1]); w.y = cvt_pk_bf16(v0[2], v0[3]); w.z = cvt_pk_bf16(v1[0], v1[1]); w.w = cvt_pk_bf16(v1[2], v1[3]);
;                     *(GAS u32x4*)(rowp + (size_t)bj * bjs) = w; } }
	v_mul_f32_e32 v107, v107, v171
	v_mul_f32_e32 v108, v108, v172
	v_mul_f32_e32 v109, v109, v173
	v_mul_f32_e32 v110, v110, v174
	v_mul_f32_e32 v111, v111, v175
	v_mul_f32_e32 v112, v112, v176
	v_mul_f32_e32 v113, v113, v177
	v_cvt_pk_bf16_f32 v110, v110, v111
	v_cvt_pk_bf16_f32 v111, v112, v113
	v_cvt_pk_bf16_f32 v112, v106, v107
	v_cvt_pk_bf16_f32 v113, v108, v109
	v_lshl_add_u64 v[158:159], v[156:157], 0, s[8:9]
	global_store_dwordx4 v[156:157], v[110:113], off
	v_cvt_pk_bf16_f32 v102, v102, v103
	v_cvt_pk_bf16_f32 v103, v104, v105
	v_cvt_pk_bf16_f32 v104, v98, v99
	v_cvt_pk_bf16_f32 v105, v100, v101
	global_store_dwordx4 v[158:159], v[102:105], off
	v_lshl_add_u64 v[156:157], v[156:157], 0, s[10:11]
	v_mul_f32_e32 v162, 0xbfb8aa3b, v82
	v_mul_f32_e32 v163, 0xbfb8aa3b, v83
	v_mul_f32_e32 v164, 0xbfb8aa3b, v84
	v_mul_f32_e32 v165, 0xbfb8aa3b, v85
	v_mul_f32_e32 v166, 0xbfb8aa3b, v86
	v_mul_f32_e32 v167, 0xbfb8aa3b, v87
	v_mul_f32_e32 v168, 0xbfb8aa3b, v88
	v_mul_f32_e32 v169, 0xbfb8aa3b, v89
	v_mul_f32_e32 v170, 0xbfb8aa3b, v90
	v_mul_f32_e32 v171, 0xbfb8aa3b, v91
	v_mul_f32_e32 v172, 0xbfb8aa3b, v92
	v_mul_f32_e32 v173, 0xbfb8aa3b, v93
	v_mul_f32_e32 v174, 0xbfb8aa3b, v94
	v_mul_f32_e32 v175, 0xbfb8aa3b, v95
	v_mul_f32_e32 v176, 0xbfb8aa3b, v96
	v_mul_f32_e32 v177, 0xbfb8aa3b, v97
	v_exp_f32_e32 v162, v162
	v_exp_f32_e32 v163, v163
	v_exp_f32_e32 v164, v164
	v_exp_f32_e32 v165, v165
	v_exp_f32_e32 v166, v166
	v_exp_f32_e32 v167, v167
	v_exp_f32_e32 v168, v168
	v_exp_f32_e32 v169, v169
	v_exp_f32_e32 v170, v170
	v_exp_f32_e32 v171, v171
	v_exp_f32_e32 v172, v172
	v_exp_f32_e32 v173, v173
	v_exp_f32_e32 v174, v174
	v_exp_f32_e32 v175, v175
	v_exp_f32_e32 v176, v176
	v_exp_f32_e32 v177, v177
	v_add_f32_e32 v162, 1.0, v162
	v_add_f32_e32 v163, 1.0, v163
	v_add_f32_e32 v164, 1.0, v164
	v_add_f32_e32 v165, 1.0, v165
	v_add_f32_e32 v166, 1.0, v166
	v_add_f32_e32 v167, 1.0, v167
	v_add_f32_e32 v168, 1.0, v168
	v_add_f32_e32 v169, 1.0, v169
	v_add_f32_e32 v170, 1.0, v170
	v_add_f32_e32 v171, 1.0, v171
	v_add_f32_e32 v172, 1.0, v172
	v_add_f32_e32 v173, 1.0, v173
	v_add_f32_e32 v174, 1.0, v174
	v_add_f32_e32 v175, 1.0, v175
	v_add_f32_e32 v176, 1.0, v176
	v_add_f32_e32 v177, 1.0, v177
	v_rcp_f32_e32 v162, v162
	v_rcp_f32_e32 v163, v163
	v_rcp_f32_e32 v164, v164
	v_rcp_f32_e32 v165, v165
	v_rcp_f32_e32 v166, v166
	v_rcp_f32_e32 v167, v167
	v_rcp_f32_e32 v168, v168
	v_rcp_f32_e32 v169, v169
	v_rcp_f32_e32 v170, v170
	v_rcp_f32_e32 v171, v171
	v_rcp_f32_e32 v172, v172
	v_rcp_f32_e32 v173, v173
	v_rcp_f32_e32 v174, v174
	v_rcp_f32_e32 v175, v175
	v_rcp_f32_e32 v176, v176
	v_rcp_f32_e32 v177, v177
	v_mul_f32_e32 v82, v82, v162
	v_mul_f32_e32 v83, v83, v163
	v_mul_f32_e32 v84, v84, v164
	v_mul_f32_e32 v85, v85, v165
	v_mul_f32_e32 v86, v86, v166
	v_mul_f32_e32 v87, v87, v167
	v_mul_f32_e32 v88, v88, v168
	v_mul_f32_e32 v89, v89, v169
	v_mul_f32_e32 v90, v90, v170
	v_mul_f32_e32 v91, v91, v171
	v_mul_f32_e32 v92, v92, v172
	v_mul_f32_e32 v93, v93, v173
	v_mul_f32_e32 v94, v94, v174
	v_mul_f32_e32 v95, v95, v175
	v_mul_f32_e32 v96, v96, v176
	v_mul_f32_e32 v97, v97, v177
	v_cvt_pk_bf16_f32 v94, v94, v95
	v_cvt_pk_bf16_f32 v95, v96, v97
	v_cvt_pk_bf16_f32 v96, v90, v91
	v_cvt_pk_bf16_f32 v97, v92, v93
	v_lshl_add_u64 v[158:159], v[156:157], 0, s[8:9]
	global_store_dwordx4 v[156:157], v[94:97], off
	v_cvt_pk_bf16_f32 v86, v86, v87
	v_cvt_pk_bf16_f32 v87, v88, v89
	v_cvt_pk_bf16_f32 v88, v82, v83
	v_cvt_pk_bf16_f32 v89, v84, v85
	global_store_dwordx4 v[158:159], v[86:89], off
	v_lshl_add_u64 v[156:157], v[156:157], 0, s[10:11]
	v_mul_f32_e32 v162, 0xbfb8aa3b, v66
	v_mul_f32_e32 v163, 0xbfb8aa3b, v67
	v_mul_f32_e32 v164, 0xbfb8aa3b, v68
	v_mul_f32_e32 v165, 0xbfb8aa3b, v69
	v_mul_f32_e32 v166, 0xbfb8aa3b, v70
	v_mul_f32_e32 v167, 0xbfb8aa3b, v71
	v_mul_f32_e32 v168, 0xbfb8aa3b, v72
	v_mul_f32_e32 v169, 0xbfb8aa3b, v73
	v_mul_f32_e32 v170, 0xbfb8aa3b, v74
	v_mul_f32_e32 v171, 0xbfb8aa3b, v75
	v_mul_f32_e32 v172, 0xbfb8aa3b, v76
	v_mul_f32_e32 v173, 0xbfb8aa3b, v77
	v_mul_f32_e32 v174, 0xbfb8aa3b, v78
	v_mul_f32_e32 v175, 0xbfb8aa3b, v79
	v_mul_f32_e32 v176, 0xbfb8aa3b, v80
	v_mul_f32_e32 v177, 0xbfb8aa3b, v81
	v_exp_f32_e32 v162, v162
	v_exp_f32_e32 v163, v163
	v_exp_f32_e32 v164, v164
	v_exp_f32_e32 v165, v165
	v_exp_f32_e32 v166, v166
	v_exp_f32_e32 v167, v167
	v_exp_f32_e32 v168, v168
	v_exp_f32_e32 v169, v169
	v_exp_f32_e32 v170, v170
	v_exp_f32_e32 v171, v171
	v_exp_f32_e32 v172, v172
	v_exp_f32_e32 v173, v173
	v_exp_f32_e32 v174, v174
	v_exp_f32_e32 v175, v175
	v_exp_f32_e32 v176, v176
	v_exp_f32_e32 v177, v177
	v_add_f32_e32 v162, 1.0, v162
	v_add_f32_e32 v163, 1.0, v163
	v_add_f32_e32 v164, 1.0, v164
	v_add_f32_e32 v165, 1.0, v165
	v_add_f32_e32 v166, 1.0, v166
	v_add_f32_e32 v167, 1.0, v167
	v_add_f32_e32 v168, 1.0, v168
	v_add_f32_e32 v169, 1.0, v169
	v_add_f32_e32 v170, 1.0, v170
	v_add_f32_e32 v171, 1.0, v171
	v_add_f32_e32 v172, 1.0, v172
	v_add_f32_e32 v173, 1.0, v173
	v_add_f32_e32 v174, 1.0, v174
	v_add_f32_e32 v175, 1.0, v175
	v_add_f32_e32 v176, 1.0, v176
	v_add_f32_e32 v177, 1.0, v177
	v_rcp_f32_e32 v162, v162
	v_rcp_f32_e32 v163, v163
	v_rcp_f32_e32 v164, v164
	v_rcp_f32_e32 v165, v165
	v_rcp_f32_e32 v166, v166
	v_rcp_f32_e32 v167, v167
	v_rcp_f32_e32 v168, v168
	v_rcp_f32_e32 v169, v169
	v_rcp_f32_e32 v170, v170
	v_rcp_f32_e32 v171, v171
	v_rcp_f32_e32 v172, v172
	v_rcp_f32_e32 v173, v173
	v_rcp_f32_e32 v174, v174
	v_rcp_f32_e32 v175, v175
	v_rcp_f32_e32 v176, v176
	v_rcp_f32_e32 v177, v177
	v_mul_f32_e32 v66, v66, v162
	v_mul_f32_e32 v67, v67, v163
	v_mul_f32_e32 v68, v68, v164
	v_mul_f32_e32 v69, v69, v165
	v_mul_f32_e32 v70, v70, v166
; #define GAS __attribute__((address_space(1)))
; __device__ __forceinline__ unsigned cvt_pk_bf16(float lo, float hi) { const f32x2_t_ v = {lo, hi}; const bf16x2_t_ b = __builtin_convertvector(v, bf16x2_t_); return __builtin_bit_cast(unsigned, b); }
; __device__ __forceinline__ float sigmoid_f(float x) { return __builtin_amdgcn_rcpf(1.0f + __builtin_amdgcn_exp2f(-x * LOG2E)); }
;     __device__ __forceinline__ void operator()(const f32x4 (&acc)[2][2][4][2], const pg8::GUnit& u, int wr, int wc, int fr, int fq) const {
;     ...
;                 for (int bj = 0; bj < 2; ++bj) { f32x4 v0 = acc[ai][bj][m][0], v1 = acc[ai][bj][m][1];
;                     if (mode == 1) {
; #pragma unroll
;                         for (int j = 0; j < 4; ++j) { v0[j] = sigmoid_f(v0[j]); v1[j] = sigmoid_f(v1[j]); } }
;                     else if (mode == 2) {
; #pragma unroll
;                         for (int j = 0; j < 4; ++j) { v0[j] = v0[j] * sigmoid_f(v0[j]); v1[j] = v1[j] * sigmoid_f(v1[j]); } }
;                     u32x4 w; w.x = cvt_pk_bf16(v0[0], v0[1]); w.y = cvt_pk_bf16(v0[2], v0[3]); w.z = cvt_pk_bf16(v1[0], v1[1]); w.w = cvt_pk_bf16(v1[2], v1[3]);
;                     *(GAS u32x4*)(rowp + (size_t)bj * bjs) = w; } }
	v_mul_f32_e32 v71, v71, v167
	v_mul_f32_e32 v72, v72, v168
	v_mul_f32_e32 v73, v73, v169
	v_mul_f32_e32 v74, v74, v170
	v_mul_f32_e32 v75, v75, v171
	v_mul_f32_e32 v76, v76, v172
	v_mul_f32_e32 v77, v77, v173
	v_mul_f32_e32 v78, v78, v174
	v_mul_f32_e32 v79, v79, v175
	v_mul_f32_e32 v80, v80, v176
	v_mul_f32_e32 v81, v81, v177
	v_cvt_pk_bf16_f32 v78, v78, v79
	v_cvt_pk_bf16_f32 v79, v80, v81
	v_cvt_pk_bf16_f32 v80, v74, v75
	v_cvt_pk_bf16_f32 v81, v76, v77
	v_lshl_add_u64 v[158:159], v[156:157], 0, s[8:9]
	global_store_dwordx4 v[156:157], v[78:81], off
	v_cvt_pk_bf16_f32 v70, v70, v71
	v_cvt_pk_bf16_f32 v71, v72, v73
	v_cvt_pk_bf16_f32 v72, v66, v67
	v_cvt_pk_bf16_f32 v73, v68, v69
	global_store_dwordx4 v[158:159], v[70:73], off
	v_mov_b64_e32 v[156:157], v[160:161]
	v_mul_f32_e32 v162, 0xbfb8aa3b, v50
	v_mul_f32_e32 v163, 0xbfb8aa3b, v51
	v_mul_f32_e32 v164, 0xbfb8aa3b, v52
	v_mul_f32_e32 v165, 0xbfb8aa3b, v53
	v_mul_f32_e32 v166, 0xbfb8aa3b, v54
	v_mul_f32_e32 v167, 0xbfb8aa3b, v55
	v_mul_f32_e32 v168, 0xbfb8aa3b, v56
	v_mul_f32_e32 v169, 0xbfb8aa3b, v57
	v_mul_f32_e32 v170, 0xbfb8aa3b, v58
	v_mul_f32_e32 v171, 0xbfb8aa3b, v59
	v_mul_f32_e32 v172, 0xbfb8aa3b, v60
	v_mul_f32_e32 v173, 0xbfb8aa3b, v61
	v_mul_f32_e32 v174, 0xbfb8aa3b, v62
	v_mul_f32_e32 v175, 0xbfb8aa3b, v63
	v_mul_f32_e32 v176, 0xbfb8aa3b, v64
	v_mul_f32_e32 v177, 0xbfb8aa3b, v65
	v_exp_f32_e32 v162, v162
	v_exp_f32_e32 v163, v163
	v_exp_f32_e32 v164, v164
	v_exp_f32_e32 v165, v165
	v_exp_f32_e32 v166, v166
	v_exp_f32_e32 v167, v167
	v_exp_f32_e32 v168, v168
	v_exp_f32_e32 v169, v169
	v_exp_f32_e32 v170, v170
	v_exp_f32_e32 v171, v171
	v_exp_f32_e32 v172, v172
	v_exp_f32_e32 v173, v173
	v_exp_f32_e32 v174, v174
	v_exp_f32_e32 v175, v175
	v_exp_f32_e32 v176, v176
	v_exp_f32_e32 v177, v177
	v_add_f32_e32 v162, 1.0, v162
	v_add_f32_e32 v163, 1.0, v163
	v_add_f32_e32 v164, 1.0, v164
	v_add_f32_e32 v165, 1.0, v165
	v_add_f32_e32 v166, 1.0, v166
	v_add_f32_e32 v167, 1.0, v167
	v_add_f32_e32 v168, 1.0, v168
	v_add_f32_e32 v169, 1.0, v169
	v_add_f32_e32 v170, 1.0, v170
	v_add_f32_e32 v171, 1.0, v171
	v_add_f32_e32 v172, 1.0, v172
	v_add_f32_e32 v173, 1.0, v173
	v_add_f32_e32 v174, 1.0, v174
	v_add_f32_e32 v175, 1.0, v175
	v_add_f32_e32 v176, 1.0, v176
	v_add_f32_e32 v177, 1.0, v177
	v_rcp_f32_e32 v162, v162
	v_rcp_f32_e32 v163, v163
	v_rcp_f32_e32 v164, v164
	v_rcp_f32_e32 v165, v165
	v_rcp_f32_e32 v166, v166
	v_rcp_f32_e32 v167, v167
	v_rcp_f32_e32 v168, v168
	v_rcp_f32_e32 v169, v169
	v_rcp_f32_e32 v170, v170
	v_rcp_f32_e32 v171, v171
	v_rcp_f32_e32 v172, v172
	v_rcp_f32_e32 v173, v173
	v_rcp_f32_e32 v174, v174
	v_rcp_f32_e32 v175, v175
	v_rcp_f32_e32 v176, v176
	v_rcp_f32_e32 v177, v177
	v_mul_f32_e32 v50, v50, v162
	v_mul_f32_e32 v51, v51, v163
	v_mul_f32_e32 v52, v52, v164
	v_mul_f32_e32 v53, v53, v165
	v_mul_f32_e32 v54, v54, v166
	v_mul_f32_e32 v55, v55, v167
	v_mul_f32_e32 v56, v56, v168
	v_mul_f32_e32 v57, v57, v169
	v_mul_f32_e32 v58, v58, v170
	v_mul_f32_e32 v59, v59, v171
	v_mul_f32_e32 v60, v60, v172
	v_mul_f32_e32 v61, v61, v173
	v_mul_f32_e32 v62, v62, v174
	v_mul_f32_e32 v63, v63, v175
	v_mul_f32_e32 v64, v64, v176
	v_mul_f32_e32 v65, v65, v177
	v_cvt_pk_bf16_f32 v62, v62, v63
	v_cvt_pk_bf16_f32 v63, v64, v65
	v_cvt_pk_bf16_f32 v64, v58, v59
	v_cvt_pk_bf16_f32 v65, v60, v61
	v_lshl_add_u64 v[158:159], v[156:157], 0, s[8:9]
	global_store_dwordx4 v[156:157], v[62:65], off
	v_cvt_pk_bf16_f32 v54, v54, v55
	v_cvt_pk_bf16_f32 v55, v56, v57
	v_cvt_pk_bf16_f32 v56, v50, v51
	v_cvt_pk_bf16_f32 v57, v52, v53
	global_store_dwordx4 v[158:159], v[54:57], off
	v_lshl_add_u64 v[156:157], v[156:157], 0, s[10:11]
	v_mul_f32_e32 v162, 0xbfb8aa3b, v34
	v_mul_f32_e32 v163, 0xbfb8aa3b, v35
	v_mul_f32_e32 v164, 0xbfb8aa3b, v36
	v_mul_f32_e32 v165, 0xbfb8aa3b, v37
	v_mul_f32_e32 v166, 0xbfb8aa3b, v38
	v_mul_f32_e32 v167, 0xbfb8aa3b, v39
	v_mul_f32_e32 v168, 0xbfb8aa3b, v40
	v_mul_f32_e32 v169, 0xbfb8aa3b, v41
	v_mul_f32_e32 v170, 0xbfb8aa3b, v42
	v_mul_f32_e32 v171, 0xbfb8aa3b, v43
	v_mul_f32_e32 v172, 0xbfb8aa3b, v44
	v_mul_f32_e32 v173, 0xbfb8aa3b, v45
	v_mul_f32_e32 v174, 0xbfb8aa3b, v46
	v_mul_f32_e32 v175, 0xbfb8aa3b, v47
	v_mul_f32_e32 v176, 0xbfb8aa3b, v48
	v_mul_f32_e32 v177, 0xbfb8aa3b, v49
	v_exp_f32_e32 v162, v162
	v_exp_f32_e32 v163, v163
	v_exp_f32_e32 v164, v164
	v_exp_f32_e32 v165, v165
	v_exp_f32_e32 v166, v166
	v_exp_f32_e32 v167, v167
	v_exp_f32_e32 v168, v168
	v_exp_f32_e32 v169, v169
	v_exp_f32_e32 v170, v170
	v_exp_f32_e32 v171, v171
	v_exp_f32_e32 v172, v172
	v_exp_f32_e32 v173, v173
	v_exp_f32_e32 v174, v174
	v_exp_f32_e32 v175, v175
	v_exp_f32_e32 v176, v176
	v_exp_f32_e32 v177, v177
	v_add_f32_e32 v162, 1.0, v162
	v_add_f32_e32 v163, 1.0, v163
	v_add_f32_e32 v164, 1.0, v164
	v_add_f32_e32 v165, 1.0, v165
	v_add_f32_e32 v166, 1.0, v166
	v_add_f32_e32 v167, 1.0, v167
	v_add_f32_e32 v168, 1.0, v168
	v_add_f32_e32 v169, 1.0, v169
	v_add_f32_e32 v170, 1.0, v170
	v_add_f32_e32 v171, 1.0, v171
	v_add_f32_e32 v172, 1.0, v172
	v_add_f32_e32 v173, 1.0, v173
	v_add_f32_e32 v174, 1.0, v174
	v_add_f32_e32 v175, 1.0, v175
	v_add_f32_e32 v176, 1.0, v176
	v_add_f32_e32 v177, 1.0, v177
	v_rcp_f32_e32 v162, v162
	v_rcp_f32_e32 v163, v163
	v_rcp_f32_e32 v164, v164
	v_rcp_f32_e32 v165, v165
	v_rcp_f32_e32 v166, v166
	v_rcp_f32_e32 v167, v167
	v_rcp_f32_e32 v168, v168
	v_rcp_f32_e32 v169, v169
	v_rcp_f32_e32 v170, v170
	v_rcp_f32_e32 v171, v171
	v_rcp_f32_e32 v172, v172
	v_rcp_f32_e32 v173, v173
	v_rcp_f32_e32 v174, v174
	v_rcp_f32_e32 v175, v175
	v_rcp_f32_e32 v176, v176
	v_rcp_f32_e32 v177, v177
	v_mul_f32_e32 v34, v34, v162
	v_mul_f32_e32 v35, v35, v163
	v_mul_f32_e32 v36, v36, v164
; #define GAS __attribute__((address_space(1)))
; __device__ __forceinline__ unsigned cvt_pk_bf16(float lo, float hi) { const f32x2_t_ v = {lo, hi}; const bf16x2_t_ b = __builtin_convertvector(v, bf16x2_t_); return __builtin_bit_cast(unsigned, b); }
; __device__ __forceinline__ float sigmoid_f(float x) { return __builtin_amdgcn_rcpf(1.0f + __builtin_amdgcn_exp2f(-x * LOG2E)); }
;     __device__ __forceinline__ void operator()(const f32x4 (&acc)[2][2][4][2], const pg8::GUnit& u, int wr, int wc, int fr, int fq) const {
;     ...
;                 for (int bj = 0; bj < 2; ++bj) { f32x4 v0 = acc[ai][bj][m][0], v1 = acc[ai][bj][m][1];
;                     if (mode == 1) {
; #pragma unroll
;                         for (int j = 0; j < 4; ++j) { v0[j] = sigmoid_f(v0[j]); v1[j] = sigmoid_f(v1[j]); } }
;                     else if (mode == 2) {
; #pragma unroll
;                         for (int j = 0; j < 4; ++j) { v0[j] = v0[j] * sigmoid_f(v0[j]); v1[j] = v1[j] * sigmoid_f(v1[j]); } }
;                     u32x4 w; w.x = cvt_pk_bf16(v0[0], v0[1]); w.y = cvt_pk_bf16(v0[2], v0[3]); w.z = cvt_pk_bf16(v1[0], v1[1]); w.w = cvt_pk_bf16(v1[2], v1[3]);
;                     *(GAS u32x4*)(rowp + (size_t)bj * bjs) = w; } }
	v_mul_f32_e32 v37, v37, v165
	v_mul_f32_e32 v38, v38, v166
	v_mul_f32_e32 v39, v39, v167
	v_mul_f32_e32 v40, v40, v168
	v_mul_f32_e32 v41, v41, v169
	v_mul_f32_e32 v42, v42, v170
	v_mul_f32_e32 v43, v43, v171
	v_mul_f32_e32 v44, v44, v172
	v_mul_f32_e32 v45, v45, v173
	v_mul_f32_e32 v46, v46, v174
	v_mul_f32_e32 v47, v47, v175
	v_mul_f32_e32 v48, v48, v176
	v_mul_f32_e32 v49, v49, v177
	v_cvt_pk_bf16_f32 v46, v46, v47
	v_cvt_pk_bf16_f32 v47, v48, v49
	v_cvt_pk_bf16_f32 v48, v42, v43
	v_cvt_pk_bf16_f32 v49, v44, v45
	v_lshl_add_u64 v[158:159], v[156:157], 0, s[8:9]
	global_store_dwordx4 v[156:157], v[46:49], off
	v_cvt_pk_bf16_f32 v38, v38, v39
	v_cvt_pk_bf16_f32 v39, v40, v41
	v_cvt_pk_bf16_f32 v40, v34, v35
	v_cvt_pk_bf16_f32 v41, v36, v37
	global_store_dwordx4 v[158:159], v[38:41], off
	v_lshl_add_u64 v[156:157], v[156:157], 0, s[10:11]
	v_mul_f32_e32 v162, 0xbfb8aa3b, v18
	v_mul_f32_e32 v163, 0xbfb8aa3b, v19
	v_mul_f32_e32 v164, 0xbfb8aa3b, v20
	v_mul_f32_e32 v165, 0xbfb8aa3b, v21
	v_mul_f32_e32 v166, 0xbfb8aa3b, v22
	v_mul_f32_e32 v167, 0xbfb8aa3b, v23
	v_mul_f32_e32 v168, 0xbfb8aa3b, v24
	v_mul_f32_e32 v169, 0xbfb8aa3b, v25
	v_mul_f32_e32 v170, 0xbfb8aa3b, v26
	v_mul_f32_e32 v171, 0xbfb8aa3b, v27
	v_mul_f32_e32 v172, 0xbfb8aa3b, v28
	v_mul_f32_e32 v173, 0xbfb8aa3b, v29
	v_mul_f32_e32 v174, 0xbfb8aa3b, v30
	v_mul_f32_e32 v175, 0xbfb8aa3b, v31
	v_mul_f32_e32 v176, 0xbfb8aa3b, v32
	v_mul_f32_e32 v177, 0xbfb8aa3b, v33
	v_exp_f32_e32 v162, v162
	v_exp_f32_e32 v163, v163
	v_exp_f32_e32 v164, v164
	v_exp_f32_e32 v165, v165
	v_exp_f32_e32 v166, v166
	v_exp_f32_e32 v167, v167
	v_exp_f32_e32 v168, v168
	v_exp_f32_e32 v169, v169
	v_exp_f32_e32 v170, v170
	v_exp_f32_e32 v171, v171
	v_exp_f32_e32 v172, v172
	v_exp_f32_e32 v173, v173
	v_exp_f32_e32 v174, v174
	v_exp_f32_e32 v175, v175
	v_exp_f32_e32 v176, v176
	v_exp_f32_e32 v177, v177
	v_add_f32_e32 v162, 1.0, v162
	v_add_f32_e32 v163, 1.0, v163
	v_add_f32_e32 v164, 1.0, v164
	v_add_f32_e32 v165, 1.0, v165
	v_add_f32_e32 v166, 1.0, v166
	v_add_f32_e32 v167, 1.0, v167
	v_add_f32_e32 v168, 1.0, v168
	v_add_f32_e32 v169, 1.0, v169
	v_add_f32_e32 v170, 1.0, v170
	v_add_f32_e32 v171, 1.0, v171
	v_add_f32_e32 v172, 1.0, v172
	v_add_f32_e32 v173, 1.0, v173
	v_add_f32_e32 v174, 1.0, v174
	v_add_f32_e32 v175, 1.0, v175
	v_add_f32_e32 v176, 1.0, v176
	v_add_f32_e32 v177, 1.0, v177
	v_rcp_f32_e32 v162, v162
	v_rcp_f32_e32 v163, v163
	v_rcp_f32_e32 v164, v164
	v_rcp_f32_e32 v165, v165
	v_rcp_f32_e32 v166, v166
	v_rcp_f32_e32 v167, v167
	v_rcp_f32_e32 v168, v168
	v_rcp_f32_e32 v169, v169
	v_rcp_f32_e32 v170, v170
	v_rcp_f32_e32 v171, v171
	v_rcp_f32_e32 v172, v172
	v_rcp_f32_e32 v173, v173
	v_rcp_f32_e32 v174, v174
	v_rcp_f32_e32 v175, v175
	v_rcp_f32_e32 v176, v176
	v_rcp_f32_e32 v177, v177
	v_mul_f32_e32 v18, v18, v162
	v_mul_f32_e32 v19, v19, v163
	v_mul_f32_e32 v20, v20, v164
	v_mul_f32_e32 v21, v21, v165
	v_mul_f32_e32 v22, v22, v166
	v_mul_f32_e32 v23, v23, v167
	v_mul_f32_e32 v24, v24, v168
	v_mul_f32_e32 v25, v25, v169
	v_mul_f32_e32 v26, v26, v170
	v_mul_f32_e32 v27, v27, v171
	v_mul_f32_e32 v28, v28, v172
	v_mul_f32_e32 v29, v29, v173
	v_mul_f32_e32 v30, v30, v174
	v_mul_f32_e32 v31, v31, v175
	v_mul_f32_e32 v32, v32, v176
	v_mul_f32_e32 v33, v33, v177
	v_cvt_pk_bf16_f32 v30, v30, v31
	v_cvt_pk_bf16_f32 v31, v32, v33
	v_cvt_pk_bf16_f32 v32, v26, v27
	v_cvt_pk_bf16_f32 v33, v28, v29
	v_lshl_add_u64 v[158:159], v[156:157], 0, s[8:9]
	global_store_dwordx4 v[156:157], v[30:33], off
	v_cvt_pk_bf16_f32 v22, v22, v23
	v_cvt_pk_bf16_f32 v23, v24, v25
	v_cvt_pk_bf16_f32 v24, v18, v19
	v_cvt_pk_bf16_f32 v25, v20, v21
	global_store_dwordx4 v[158:159], v[22:25], off
	v_lshl_add_u64 v[156:157], v[156:157], 0, s[10:11]
	v_mul_f32_e32 v162, 0xbfb8aa3b, v2
	v_mul_f32_e32 v163, 0xbfb8aa3b, v3
	v_mul_f32_e32 v164, 0xbfb8aa3b, v4
	v_mul_f32_e32 v165, 0xbfb8aa3b, v5
	v_mul_f32_e32 v166, 0xbfb8aa3b, v6
	v_mul_f32_e32 v167, 0xbfb8aa3b, v7
	v_mul_f32_e32 v168, 0xbfb8aa3b, v8
	v_mul_f32_e32 v169, 0xbfb8aa3b, v9
	v_mul_f32_e32 v170, 0xbfb8aa3b, v10
	v_mul_f32_e32 v171, 0xbfb8aa3b, v11
	v_mul_f32_e32 v172, 0xbfb8aa3b, v12
	v_mul_f32_e32 v173, 0xbfb8aa3b, v13
	v_mul_f32_e32 v174, 0xbfb8aa3b, v14
	v_mul_f32_e32 v175, 0xbfb8aa3b, v15
	v_mul_f32_e32 v176, 0xbfb8aa3b, v16
	v_mul_f32_e32 v177, 0xbfb8aa3b, v17
	v_exp_f32_e32 v162, v162
	v_exp_f32_e32 v163, v163
	v_exp_f32_e32 v164, v164
	v_exp_f32_e32 v165, v165
	v_exp_f32_e32 v166, v166
	v_exp_f32_e32 v167, v167
	v_exp_f32_e32 v168, v168
	v_exp_f32_e32 v169, v169
	v_exp_f32_e32 v170, v170
	v_exp_f32_e32 v171, v171
	v_exp_f32_e32 v172, v172
	v_exp_f32_e32 v173, v173
	v_exp_f32_e32 v174, v174
	v_exp_f32_e32 v175, v175
	v_exp_f32_e32 v176, v176
	v_exp_f32_e32 v177, v177
	v_add_f32_e32 v162, 1.0, v162
	v_add_f32_e32 v163, 1.0, v163
	v_add_f32_e32 v164, 1.0, v164
	v_add_f32_e32 v165, 1.0, v165
	v_add_f32_e32 v166, 1.0, v166
	v_add_f32_e32 v167, 1.0, v167
	v_add_f32_e32 v168, 1.0, v168
	v_add_f32_e32 v169, 1.0, v169
	v_add_f32_e32 v170, 1.0, v170
	v_add_f32_e32 v171, 1.0, v171
	v_add_f32_e32 v172, 1.0, v172
	v_add_f32_e32 v173, 1.0, v173
	v_add_f32_e32 v174, 1.0, v174
	v_add_f32_e32 v175, 1.0, v175
	v_add_f32_e32 v176, 1.0, v176
	v_add_f32_e32 v177, 1.0, v177
	v_rcp_f32_e32 v162, v162
	v_rcp_f32_e32 v163, v163
	v_rcp_f32_e32 v164, v164
	v_rcp_f32_e32 v165, v165
	v_rcp_f32_e32 v166, v166
	v_rcp_f32_e32 v167, v167
	v_rcp_f32_e32 v168, v168
	v_rcp_f32_e32 v169, v169
	v_rcp_f32_e32 v170, v170
	v_rcp_f32_e32 v171, v171
	v_rcp_f32_e32 v172, v172
	v_rcp_f32_e32 v173, v173
	v_rcp_f32_e32 v174, v174
	v_rcp_f32_e32 v175, v175
	v_rcp_f32_e32 v176, v176
	v_rcp_f32_e32 v177, v177
	v_mul_f32_e32 v2, v2, v162
	v_mul_f32_e32 v3, v3, v163
	v_mul_f32_e32 v4, v4, v164
	v_mul_f32_e32 v5, v5, v165
	v_mul_f32_e32 v6, v6, v166
	v_mul_f32_e32 v7, v7, v167
	v_mul_f32_e32 v8, v8, v168
	v_mul_f32_e32 v9, v9, v169
	v_mul_f32_e32 v10, v10, v170
	v_mul_f32_e32 v11, v11, v171
	v_mul_f32_e32 v12, v12, v172
	v_mul_f32_e32 v13, v13, v173
	v_mul_f32_e32 v14, v14, v174
	v_mul_f32_e32 v15, v15, v175
	v_mul_f32_e32 v16, v16, v176
	v_mul_f32_e32 v17, v17, v177
	v_cvt_pk_bf16_f32 v14, v14, v15
	v_cvt_pk_bf16_f32 v15, v16, v17
	v_cvt_pk_bf16_f32 v16, v10, v11
	v_cvt_pk_bf16_f32 v17, v12, v13
	v_lshl_add_u64 v[158:159], v[156:157], 0, s[8:9]
	global_store_dwordx4 v[156:157], v[14:17], off
	v_cvt_pk_bf16_f32 v6, v6, v7
	v_cvt_pk_bf16_f32 v7, v8, v9
	v_cvt_pk_bf16_f32 v8, v2, v3
	v_cvt_pk_bf16_f32 v9, v4, v5
	global_store_dwordx4 v[158:159], v[6:9], off
	v_mov_b32_e32 v126, v210
	s_and_b64 vcc, exec, s[36:37]
	s_mov_b32 s18, s88
	s_mov_b32 s12, s87
	s_mov_b32 s13, s89
	s_mov_b32 s10, s91
	s_mov_b32 s11, s90
	s_cbranch_vccnz .LBB0_401
	s_branch .LBB0_273

; __device__ __forceinline__ float sigmoid_f(float x) { return __builtin_amdgcn_rcpf(1.0f + __builtin_amdgcn_exp2f(-x * LOG2E)); }
;     __device__ __forceinline__ void operator()(const f32x4 (&acc)[2][2][4][2], const pg8::GUnit& u, int wr, int wc, int fr, int fq) const {
;     ...
;                     if (mode == 1) {
; #pragma unroll
;                         for (int j = 0; j < 4; ++j) { v0[j] = sigmoid_f(v0[j]); v1[j] = sigmoid_f(v1[j]); } }
;                     else if (mode == 2) {
; #pragma unroll
;                         for (int j = 0; j < 4; ++j) { v0[j] = v0[j] * sigmoid_f(v0[j]); v1[j] = v1[j] * sigmoid_f(v1[j]); } }
.LBB0_303:
	s_branch .Lin_epi_fast_silu
	v_mul_f32_e32 v140, 0xbfb8aa3b, v126
	v_exp_f32_e32 v140, v140
	v_mul_f32_e32 v141, 0xbfb8aa3b, v122
	v_mul_f32_e32 v142, 0xbfb8aa3b, v127
	v_exp_f32_e32 v141, v141
	v_exp_f32_e32 v143, v142
	v_add_f32_e32 v140, 1.0, v140
	v_rcp_f32_e32 v142, v140
	v_add_f32_e32 v140, 1.0, v141
	v_rcp_f32_e32 v146, v140
	v_add_f32_e32 v140, 1.0, v143
	v_rcp_f32_e32 v143, v140
	v_mul_f32_e32 v140, 0xbfb8aa3b, v123
	v_mul_f32_e32 v141, 0xbfb8aa3b, v128
	v_mul_f32_e32 v144, 0xbfb8aa3b, v124
	v_exp_f32_e32 v140, v140
	v_exp_f32_e32 v141, v141
	v_exp_f32_e32 v144, v144
	v_pk_mul_f32 v[142:143], v[126:127], v[142:143]
	v_add_f32_e32 v147, 1.0, v140
	v_add_f32_e32 v140, 1.0, v141
	v_add_f32_e32 v141, 1.0, v144
	v_mul_f32_e32 v144, 0xbfb8aa3b, v129
	v_exp_f32_e32 v145, v144
	v_mul_f32_e32 v144, 0xbfb8aa3b, v125
	v_exp_f32_e32 v154, v144
	v_rcp_f32_e32 v144, v141
	v_add_f32_e32 v141, 1.0, v145
	v_rcp_f32_e32 v140, v140
	v_add_f32_e32 v145, 1.0, v154
	v_rcp_f32_e32 v141, v141
	v_rcp_f32_e32 v145, v145
	v_rcp_f32_e32 v147, v147
	s_mov_b64 s[10:11], 0
	v_pk_mul_f32 v[140:141], v[128:129], v[140:141]
	v_pk_mul_f32 v[144:145], v[124:125], v[144:145]
	v_pk_mul_f32 v[146:147], v[122:123], v[146:147]
.LBB0_304:
	s_cmp_eq_u32 s96, 0
	s_cbranch_scc1 .Lin_epi_fast
	s_andn2_b64 vcc, exec, s[10:11]
	s_cbranch_vccnz .LBB0_308
	s_cmp_eq_u32 s96, 1
	s_cbranch_scc0 .LBB0_307
	v_mul_f32_e32 v126, 0xbfb8aa3b, v126
	v_mul_f32_e32 v122, 0xbfb8aa3b, v122
	v_mul_f32_e32 v127, 0xbfb8aa3b, v127
	v_mul_f32_e32 v123, 0xbfb8aa3b, v123
	v_mul_f32_e32 v128, 0xbfb8aa3b, v128
	v_mul_f32_e32 v124, 0xbfb8aa3b, v124
	v_mul_f32_e32 v129, 0xbfb8aa3b, v129
	v_mul_f32_e32 v125, 0xbfb8aa3b, v125
	v_exp_f32_e32 v126, v126
	v_exp_f32_e32 v122, v122
	v_exp_f32_e32 v127, v127
	v_exp_f32_e32 v123, v123
	v_exp_f32_e32 v128, v128
	v_exp_f32_e32 v124, v124
	v_exp_f32_e32 v129, v129
	v_exp_f32_e32 v125, v125
	v_add_f32_e32 v126, 1.0, v126
	v_add_f32_e32 v122, 1.0, v122
	v_add_f32_e32 v127, 1.0, v127
	v_add_f32_e32 v123, 1.0, v123
	v_add_f32_e32 v128, 1.0, v128
	v_add_f32_e32 v124, 1.0, v124
	v_add_f32_e32 v129, 1.0, v129
	v_add_f32_e32 v125, 1.0, v125
	v_rcp_f32_e32 v126, v126
	v_rcp_f32_e32 v122, v122
	v_rcp_f32_e32 v127, v127
	v_rcp_f32_e32 v123, v123
	v_rcp_f32_e32 v128, v128
	v_rcp_f32_e32 v124, v124
	v_rcp_f32_e32 v129, v129
	v_rcp_f32_e32 v125, v125
